# v22 + separate first-tile / later-tile copies of the peeled K-loop head; the later-tile copy's two vmcnt(8) waits relaxed to 16/24 so the leading half does not wait on epilogue store acks before its f
# baseline (speedup 1.0000x reference)
; #define PG8_STAGE(bufoff, gbase, voff) do { _Pragma("unroll") for (int _i = 0; _i < 2; ++_i) \
;         __builtin_amdgcn_global_load_lds((const unsigned*)((const char*)(gbase) + (voff)[_i]), (LAS unsigned*)(lds + (bufoff) + ldsw + _i * 8192), 16, 0, 0); } while (0)
; #define PG8_LDA(dst, b, h) do { _Pragma("unroll") for (int m = 0; m < 4; ++m) _Pragma("unroll") for (int k = 0; k < 2; ++k) dst[m][k] = *(const LAS bf16x8*)(lds + PG8_SA(b, h) + aoff + m * 2048 + k * 1024); } while (0)
; #define PG8_LDB(dst, b, h) do { _Pragma("unroll") for (int n = 0; n < 2; ++n) _Pragma("unroll") for (int k = 0; k < 2; ++k) dst[n][k] = *(const LAS bf16x8*)(lds + PG8_SB(b, h) + boff + n * 2048 + k * 1024); } while (0)
; #define PG8_MMA(ai, bj, At, Bt) do { __builtin_amdgcn_s_setprio(1); _Pragma("unroll") for (int m = 0; m < 4; ++m) _Pragma("unroll") for (int n = 0; n < 2; ++n) _Pragma("unroll") for (int k = 0; k < 2; ++k) \
;         acc[ai][bj][m][n] = __builtin_amdgcn_mfma_f32_16x16x32_bf16(Bt[n][k], At[m][k], acc[ai][bj][m][n], 0, 0, 0); __builtin_amdgcn_s_setprio(0); } while (0)
; #define PG8_WAIT_V(n) asm volatile("s_waitcnt vmcnt(" #n ")" ::: "memory")
; #define PG8_WAIT_L(n) asm volatile("s_waitcnt lgkmcnt(" #n ")" ::: "memory")
; #define PG8_BAR __builtin_amdgcn_s_barrier()
; #define PG8_SCHED __builtin_amdgcn_sched_barrier(0)
; template <class Epi, class Sched>
; __device__ __forceinline__ void gemm_phase(LAS unsigned char* lds, const int lda, const int ldb, const int K, const Sched& S, const Epi& E) {
;     ...
;         for (int t = 0; t < nt; t += 2) {
;             const bool last = (t == nt - 2);
;             const char* a1 = cA + (size_t)(t + 1) * kstep;
;             const char* a2 = last ? nA : cA + (size_t)(t + 2) * kstep; const char* b2 = last ? nB : cB + (size_t)(t + 2) * kstep;
;             const char* a3 = a2 + kstep; const char* b3 = b2 + kstep;
;             PG8_LDB(B0, 0, 0); PG8_LDB(B1, 0, 1); PG8_SCHED; PG8_LDA(At, 0, 0); PG8_STAGE(PG8_SA(1, 1), a1 + hstepA, voffA);
;             PG8_WAIT_V(8); PG8_WAIT_L(0); PG8_BAR; PG8_MMA(0, 0, At, B0); PG8_MMA(0, 1, At, B1); PG8_BAR; PG8_SCHED;
;             PG8_LDA(At, 0, 1); PG8_STAGE(PG8_SB(0, 0), b2, voffB); PG8_STAGE(PG8_SB(0, 1), b2 + hstepB, voffB); PG8_STAGE(PG8_SA(0, 0), a2, voffA);
;             PG8_WAIT_V(8); PG8_WAIT_L(0); PG8_BAR; PG8_MMA(1, 0, At, B0); PG8_MMA(1, 1, At, B1); PG8_BAR; PG8_SCHED;
.LBB0_240:
	s_lshl_b32 s20, s20, 8
	s_ashr_i32 s21, s20, 31
	s_add_u32 s22, s22, 0x40080
	s_addc_u32 s23, s23, 0
	s_add_u32 s13, s24, 0x100
	s_addc_u32 s15, s25, 0
	s_mov_b32 s65, -2
	v_lshl_add_u64 v[214:215], s[20:21], 2, v[204:205]
	v_add_u32_e32 v230, 0x80, v200
	v_add_u32_e32 v231, 0x80, v196
	v_add_u32_e32 v232, 0x80, v202
	v_add_u32_e32 v233, 0x80, v198
	s_cmp_eq_u32 s41, 1
	s_cbranch_scc1 .Lpeel1_first
	s_add_u32 s21, s22, 0xfffc0080
	s_addc_u32 s24, s23, -1
	s_cmp_eq_u32 s65, 12
	s_cselect_b32 s29, s17, s24
	s_cselect_b32 s28, s16, s21
	s_cselect_b32 s31, s19, s15
	s_cselect_b32 s30, s18, s13
	s_add_i32 s72, s50, s3
	s_add_i32 m0, s37, 0xc000
	s_add_i32 s71, s37, 0xe000
	s_add_i32 s73, s72, 0x2000
	s_add_u32 s48, s30, 0x40000
	s_addc_u32 s49, s31, 0
	s_add_i32 s74, s51, s3
	s_add_i32 s75, s74, 0x2000
	s_add_i32 s76, 0, 0x18000
	s_add_i32 s77, 0, 0x1c000
	s_add_u32 s26, s28, 0x40000
	s_addc_u32 s27, s29, 0
	s_add_i32 s68, s76, s3
	s_add_i32 s21, s68, 0x2000
	s_add_u32 s24, s30, 0x40080
	s_addc_u32 s25, s31, 0
	s_add_i32 s70, s77, s3
	s_add_i32 s69, s70, 0x2000
	s_cmp_lg_u32 s65, 12
	global_load_lds_dwordx4 v206, s[22:23]
	s_mov_b32 m0, s71
	s_nop 0
	global_load_lds_dwordx4 v208, s[22:23]
	s_waitcnt vmcnt(16)
	s_waitcnt lgkmcnt(0)
	s_barrier
	v_mfma_f32_16x16x32_bf16 v[126:129], v[130:133], v[162:165], 0
	v_mfma_f32_16x16x32_bf16 v[118:121], v[138:141], v[162:165], 0
	v_mfma_f32_16x16x32_bf16 v[110:113], v[130:133], v[170:173], 0
	v_mfma_f32_16x16x32_bf16 v[102:105], v[138:141], v[170:173], 0
	v_mfma_f32_16x16x32_bf16 v[94:97], v[130:133], v[178:181], 0
	v_mfma_f32_16x16x32_bf16 v[86:89], v[138:141], v[178:181], 0
	v_mfma_f32_16x16x32_bf16 v[78:81], v[130:133], v[186:189], 0
	v_mfma_f32_16x16x32_bf16 v[70:73], v[138:141], v[186:189], 0
	v_mfma_f32_16x16x32_bf16 v[126:129], v[134:137], v[166:169], v[126:129]
	v_mfma_f32_16x16x32_bf16 v[118:121], v[142:145], v[166:169], v[118:121]
	v_mfma_f32_16x16x32_bf16 v[110:113], v[134:137], v[174:177], v[110:113]
	v_mfma_f32_16x16x32_bf16 v[102:105], v[142:145], v[174:177], v[102:105]
	v_mfma_f32_16x16x32_bf16 v[94:97], v[134:137], v[182:185], v[94:97]
	v_mfma_f32_16x16x32_bf16 v[86:89], v[142:145], v[182:185], v[86:89]
	v_mfma_f32_16x16x32_bf16 v[78:81], v[134:137], v[190:193], v[78:81]
	v_mfma_f32_16x16x32_bf16 v[70:73], v[142:145], v[190:193], v[70:73]
	v_mfma_f32_16x16x32_bf16 v[122:125], v[146:149], v[162:165], 0
	v_mfma_f32_16x16x32_bf16 v[114:117], v[154:157], v[162:165], 0
	v_mfma_f32_16x16x32_bf16 v[106:109], v[146:149], v[170:173], 0
	v_mfma_f32_16x16x32_bf16 v[98:101], v[154:157], v[170:173], 0
	v_mfma_f32_16x16x32_bf16 v[90:93], v[146:149], v[178:181], 0
	v_mfma_f32_16x16x32_bf16 v[82:85], v[154:157], v[178:181], 0
	v_mfma_f32_16x16x32_bf16 v[74:77], v[146:149], v[186:189], 0
	v_mfma_f32_16x16x32_bf16 v[66:69], v[154:157], v[186:189], 0
	v_mfma_f32_16x16x32_bf16 v[122:125], v[150:153], v[166:169], v[122:125]
	v_mfma_f32_16x16x32_bf16 v[114:117], v[158:161], v[166:169], v[114:117]
	v_mfma_f32_16x16x32_bf16 v[106:109], v[150:153], v[174:177], v[106:109]
	v_mfma_f32_16x16x32_bf16 v[98:101], v[158:161], v[174:177], v[98:101]
	v_mfma_f32_16x16x32_bf16 v[90:93], v[150:153], v[182:185], v[90:93]
	v_mfma_f32_16x16x32_bf16 v[82:85], v[158:161], v[182:185], v[82:85]
	v_mfma_f32_16x16x32_bf16 v[74:77], v[150:153], v[190:193], v[74:77]
	v_mfma_f32_16x16x32_bf16 v[66:69], v[158:161], v[190:193], v[66:69]
	s_barrier
	s_mov_b32 m0, s72
	ds_read_b128 v[162:165], v219 offset:16384
	ds_read_b128 v[166:169], v219 offset:17408
	ds_read_b128 v[170:173], v219 offset:18432
	ds_read_b128 v[174:177], v219 offset:19456
	ds_read_b128 v[178:181], v219 offset:20480
	ds_read_b128 v[182:185], v219 offset:21504
	ds_read_b128 v[186:189], v219 offset:22528
	ds_read_b128 v[190:193], v219 offset:23552
	global_load_lds_dwordx4 v200, s[30:31]
	s_mov_b32 m0, s73
	s_nop 0
	global_load_lds_dwordx4 v196, s[30:31]
	s_mov_b32 m0, s74
	s_nop 0
	global_load_lds_dwordx4 v200, s[48:49]
	s_mov_b32 m0, s75
	s_nop 0
	global_load_lds_dwordx4 v196, s[48:49]
	s_mov_b32 m0, s37
	s_nop 0
	global_load_lds_dwordx4 v202, s[28:29]
	s_mov_b32 m0, s38
	s_nop 0
	global_load_lds_dwordx4 v198, s[28:29]
	s_waitcnt vmcnt(16)
	s_waitcnt lgkmcnt(0)
	s_barrier
	v_mfma_f32_16x16x32_bf16 v[62:65], v[130:133], v[162:165], 0
	v_mfma_f32_16x16x32_bf16 v[54:57], v[138:141], v[162:165], 0
	v_mfma_f32_16x16x32_bf16 v[46:49], v[130:133], v[170:173], 0
	v_mfma_f32_16x16x32_bf16 v[38:41], v[138:141], v[170:173], 0
	v_mfma_f32_16x16x32_bf16 v[30:33], v[130:133], v[178:181], 0
	v_mfma_f32_16x16x32_bf16 v[22:25], v[138:141], v[178:181], 0
	v_mfma_f32_16x16x32_bf16 v[14:17], v[130:133], v[186:189], 0
	v_mfma_f32_16x16x32_bf16 v[6:9], v[138:141], v[186:189], 0
	v_mfma_f32_16x16x32_bf16 v[62:65], v[134:137], v[166:169], v[62:65]
	v_mfma_f32_16x16x32_bf16 v[54:57], v[142:145], v[166:169], v[54:57]
	v_mfma_f32_16x16x32_bf16 v[46:49], v[134:137], v[174:177], v[46:49]
	v_mfma_f32_16x16x32_bf16 v[38:41], v[142:145], v[174:177], v[38:41]
	v_mfma_f32_16x16x32_bf16 v[30:33], v[134:137], v[182:185], v[30:33]
	v_mfma_f32_16x16x32_bf16 v[22:25], v[142:145], v[182:185], v[22:25]
	v_mfma_f32_16x16x32_bf16 v[14:17], v[134:137], v[190:193], v[14:17]
	v_mfma_f32_16x16x32_bf16 v[6:9], v[142:145], v[190:193], v[6:9]
	v_mfma_f32_16x16x32_bf16 v[58:61], v[146:149], v[162:165], 0
	v_mfma_f32_16x16x32_bf16 v[50:53], v[154:157], v[162:165], 0
	v_mfma_f32_16x16x32_bf16 v[42:45], v[146:149], v[170:173], 0
	v_mfma_f32_16x16x32_bf16 v[34:37], v[154:157], v[170:173], 0
	v_mfma_f32_16x16x32_bf16 v[26:29], v[146:149], v[178:181], 0
	v_mfma_f32_16x16x32_bf16 v[18:21], v[154:157], v[178:181], 0
	v_mfma_f32_16x16x32_bf16 v[10:13], v[146:149], v[186:189], 0
	v_mfma_f32_16x16x32_bf16 v[2:5], v[154:157], v[186:189], 0
	v_mfma_f32_16x16x32_bf16 v[58:61], v[150:153], v[166:169], v[58:61]
	v_mfma_f32_16x16x32_bf16 v[50:53], v[158:161], v[166:169], v[50:53]
	v_mfma_f32_16x16x32_bf16 v[42:45], v[150:153], v[174:177], v[42:45]
	v_mfma_f32_16x16x32_bf16 v[34:37], v[158:161], v[174:177], v[34:37]
	v_mfma_f32_16x16x32_bf16 v[26:29], v[150:153], v[182:185], v[26:29]
	v_mfma_f32_16x16x32_bf16 v[18:21], v[158:161], v[182:185], v[18:21]
	v_mfma_f32_16x16x32_bf16 v[10:13], v[150:153], v[190:193], v[10:13]
	v_mfma_f32_16x16x32_bf16 v[2:5], v[158:161], v[190:193], v[2:5]
	s_barrier
	s_branch .Lpeel1_join
; #define PG8_STAGE(bufoff, gbase, voff) do { _Pragma("unroll") for (int _i = 0; _i < 2; ++_i) \
;         __builtin_amdgcn_global_load_lds((const unsigned*)((const char*)(gbase) + (voff)[_i]), (LAS unsigned*)(lds + (bufoff) + ldsw + _i * 8192), 16, 0, 0); } while (0)
; #define PG8_LDA(dst, b, h) do { _Pragma("unroll") for (int m = 0; m < 4; ++m) _Pragma("unroll") for (int k = 0; k < 2; ++k) dst[m][k] = *(const LAS bf16x8*)(lds + PG8_SA(b, h) + aoff + m * 2048 + k * 1024); } while (0)
; #define PG8_LDB(dst, b, h) do { _Pragma("unroll") for (int n = 0; n < 2; ++n) _Pragma("unroll") for (int k = 0; k < 2; ++k) dst[n][k] = *(const LAS bf16x8*)(lds + PG8_SB(b, h) + boff + n * 2048 + k * 1024); } while (0)
; #define PG8_MMA(ai, bj, At, Bt) do { __builtin_amdgcn_s_setprio(1); _Pragma("unroll") for (int m = 0; m < 4; ++m) _Pragma("unroll") for (int n = 0; n < 2; ++n) _Pragma("unroll") for (int k = 0; k < 2; ++k) \
;         acc[ai][bj][m][n] = __builtin_amdgcn_mfma_f32_16x16x32_bf16(Bt[n][k], At[m][k], acc[ai][bj][m][n], 0, 0, 0); __builtin_amdgcn_s_setprio(0); } while (0)
; #define PG8_WAIT_V(n) asm volatile("s_waitcnt vmcnt(" #n ")" ::: "memory")
; #define PG8_WAIT_L(n) asm volatile("s_waitcnt lgkmcnt(" #n ")" ::: "memory")
; #define PG8_BAR __builtin_amdgcn_s_barrier()
; #define PG8_SCHED __builtin_amdgcn_sched_barrier(0)
; template <class Epi, class Sched>
; __device__ __forceinline__ void gemm_phase(LAS unsigned char* lds, const int lda, const int ldb, const int K, const Sched& S, const Epi& E) {
;     ...
;         for (int t = 0; t < nt; t += 2) {
;             const bool last = (t == nt - 2);
;             const char* a1 = cA + (size_t)(t + 1) * kstep;
;             const char* a2 = last ? nA : cA + (size_t)(t + 2) * kstep; const char* b2 = last ? nB : cB + (size_t)(t + 2) * kstep;
;             const char* a3 = a2 + kstep; const char* b3 = b2 + kstep;
;             PG8_LDB(B0, 0, 0); PG8_LDB(B1, 0, 1); PG8_SCHED; PG8_LDA(At, 0, 0); PG8_STAGE(PG8_SA(1, 1), a1 + hstepA, voffA);
;             PG8_WAIT_V(8); PG8_WAIT_L(0); PG8_BAR; PG8_MMA(0, 0, At, B0); PG8_MMA(0, 1, At, B1); PG8_BAR; PG8_SCHED;
;             PG8_LDA(At, 0, 1); PG8_STAGE(PG8_SB(0, 0), b2, voffB); PG8_STAGE(PG8_SB(0, 1), b2 + hstepB, voffB); PG8_STAGE(PG8_SA(0, 0), a2, voffA);
;             PG8_WAIT_V(8); PG8_WAIT_L(0); PG8_BAR; PG8_MMA(1, 0, At, B0); PG8_MMA(1, 1, At, B1); PG8_BAR; PG8_SCHED;
.Lpeel1_first:
	s_add_u32 s21, s22, 0xfffc0080
	s_addc_u32 s24, s23, -1
	s_cmp_eq_u32 s65, 12
	s_cselect_b32 s29, s17, s24
	s_cselect_b32 s28, s16, s21
	s_cselect_b32 s31, s19, s15
	s_cselect_b32 s30, s18, s13
	s_add_i32 s72, s50, s3
	s_add_i32 m0, s37, 0xc000
	s_add_i32 s71, s37, 0xe000
	s_add_i32 s73, s72, 0x2000
	s_add_u32 s48, s30, 0x40000
	s_addc_u32 s49, s31, 0
	s_add_i32 s74, s51, s3
	s_add_i32 s75, s74, 0x2000
	s_add_i32 s76, 0, 0x18000
	s_add_i32 s77, 0, 0x1c000
	s_add_u32 s26, s28, 0x40000
	s_addc_u32 s27, s29, 0
	s_add_i32 s68, s76, s3
	s_add_i32 s21, s68, 0x2000
	s_add_u32 s24, s30, 0x40080
	s_addc_u32 s25, s31, 0
	s_add_i32 s70, s77, s3
	s_add_i32 s69, s70, 0x2000
	s_cmp_lg_u32 s65, 12
	global_load_lds_dwordx4 v206, s[22:23]
	s_mov_b32 m0, s71
	s_nop 0
	global_load_lds_dwordx4 v208, s[22:23]
	s_waitcnt vmcnt(8)
	s_waitcnt lgkmcnt(0)
	s_barrier
	v_mfma_f32_16x16x32_bf16 v[126:129], v[130:133], v[162:165], 0
	v_mfma_f32_16x16x32_bf16 v[118:121], v[138:141], v[162:165], 0
	v_mfma_f32_16x16x32_bf16 v[110:113], v[130:133], v[170:173], 0
	v_mfma_f32_16x16x32_bf16 v[102:105], v[138:141], v[170:173], 0
	v_mfma_f32_16x16x32_bf16 v[94:97], v[130:133], v[178:181], 0
	v_mfma_f32_16x16x32_bf16 v[86:89], v[138:141], v[178:181], 0
	v_mfma_f32_16x16x32_bf16 v[78:81], v[130:133], v[186:189], 0
	v_mfma_f32_16x16x32_bf16 v[70:73], v[138:141], v[186:189], 0
	v_mfma_f32_16x16x32_bf16 v[126:129], v[134:137], v[166:169], v[126:129]
	v_mfma_f32_16x16x32_bf16 v[118:121], v[142:145], v[166:169], v[118:121]
	v_mfma_f32_16x16x32_bf16 v[110:113], v[134:137], v[174:177], v[110:113]
	v_mfma_f32_16x16x32_bf16 v[102:105], v[142:145], v[174:177], v[102:105]
	v_mfma_f32_16x16x32_bf16 v[94:97], v[134:137], v[182:185], v[94:97]
	v_mfma_f32_16x16x32_bf16 v[86:89], v[142:145], v[182:185], v[86:89]
	v_mfma_f32_16x16x32_bf16 v[78:81], v[134:137], v[190:193], v[78:81]
	v_mfma_f32_16x16x32_bf16 v[70:73], v[142:145], v[190:193], v[70:73]
	v_mfma_f32_16x16x32_bf16 v[122:125], v[146:149], v[162:165], 0
	v_mfma_f32_16x16x32_bf16 v[114:117], v[154:157], v[162:165], 0
	v_mfma_f32_16x16x32_bf16 v[106:109], v[146:149], v[170:173], 0
	v_mfma_f32_16x16x32_bf16 v[98:101], v[154:157], v[170:173], 0
	v_mfma_f32_16x16x32_bf16 v[90:93], v[146:149], v[178:181], 0
	v_mfma_f32_16x16x32_bf16 v[82:85], v[154:157], v[178:181], 0
	v_mfma_f32_16x16x32_bf16 v[74:77], v[146:149], v[186:189], 0
	v_mfma_f32_16x16x32_bf16 v[66:69], v[154:157], v[186:189], 0
	v_mfma_f32_16x16x32_bf16 v[122:125], v[150:153], v[166:169], v[122:125]
	v_mfma_f32_16x16x32_bf16 v[114:117], v[158:161], v[166:169], v[114:117]
	v_mfma_f32_16x16x32_bf16 v[106:109], v[150:153], v[174:177], v[106:109]
	v_mfma_f32_16x16x32_bf16 v[98:101], v[158:161], v[174:177], v[98:101]
	v_mfma_f32_16x16x32_bf16 v[90:93], v[150:153], v[182:185], v[90:93]
	v_mfma_f32_16x16x32_bf16 v[82:85], v[158:161], v[182:185], v[82:85]
	v_mfma_f32_16x16x32_bf16 v[74:77], v[150:153], v[190:193], v[74:77]
	v_mfma_f32_16x16x32_bf16 v[66:69], v[158:161], v[190:193], v[66:69]
	s_barrier
	s_mov_b32 m0, s72
	ds_read_b128 v[162:165], v219 offset:16384
	ds_read_b128 v[166:169], v219 offset:17408
	ds_read_b128 v[170:173], v219 offset:18432
	ds_read_b128 v[174:177], v219 offset:19456
	ds_read_b128 v[178:181], v219 offset:20480
	ds_read_b128 v[182:185], v219 offset:21504
	ds_read_b128 v[186:189], v219 offset:22528
	ds_read_b128 v[190:193], v219 offset:23552
	global_load_lds_dwordx4 v200, s[30:31]
	s_mov_b32 m0, s73
	s_nop 0
	global_load_lds_dwordx4 v196, s[30:31]
	s_mov_b32 m0, s74
	s_nop 0
	global_load_lds_dwordx4 v200, s[48:49]
	s_mov_b32 m0, s75
	s_nop 0
	global_load_lds_dwordx4 v196, s[48:49]
	s_mov_b32 m0, s37
	s_nop 0
	global_load_lds_dwordx4 v202, s[28:29]
	s_mov_b32 m0, s38
	s_nop 0
	global_load_lds_dwordx4 v198, s[28:29]
	s_waitcnt vmcnt(8)
	s_waitcnt lgkmcnt(0)
	s_barrier
	v_mfma_f32_16x16x32_bf16 v[62:65], v[130:133], v[162:165], 0
	v_mfma_f32_16x16x32_bf16 v[54:57], v[138:141], v[162:165], 0
	v_mfma_f32_16x16x32_bf16 v[46:49], v[130:133], v[170:173], 0
	v_mfma_f32_16x16x32_bf16 v[38:41], v[138:141], v[170:173], 0
	v_mfma_f32_16x16x32_bf16 v[30:33], v[130:133], v[178:181], 0
	v_mfma_f32_16x16x32_bf16 v[22:25], v[138:141], v[178:181], 0
	v_mfma_f32_16x16x32_bf16 v[14:17], v[130:133], v[186:189], 0
	v_mfma_f32_16x16x32_bf16 v[6:9], v[138:141], v[186:189], 0
	v_mfma_f32_16x16x32_bf16 v[62:65], v[134:137], v[166:169], v[62:65]
	v_mfma_f32_16x16x32_bf16 v[54:57], v[142:145], v[166:169], v[54:57]
	v_mfma_f32_16x16x32_bf16 v[46:49], v[134:137], v[174:177], v[46:49]
	v_mfma_f32_16x16x32_bf16 v[38:41], v[142:145], v[174:177], v[38:41]
	v_mfma_f32_16x16x32_bf16 v[30:33], v[134:137], v[182:185], v[30:33]
	v_mfma_f32_16x16x32_bf16 v[22:25], v[142:145], v[182:185], v[22:25]
	v_mfma_f32_16x16x32_bf16 v[14:17], v[134:137], v[190:193], v[14:17]
	v_mfma_f32_16x16x32_bf16 v[6:9], v[142:145], v[190:193], v[6:9]
	v_mfma_f32_16x16x32_bf16 v[58:61], v[146:149], v[162:165], 0
	v_mfma_f32_16x16x32_bf16 v[50:53], v[154:157], v[162:165], 0
	v_mfma_f32_16x16x32_bf16 v[42:45], v[146:149], v[170:173], 0
	v_mfma_f32_16x16x32_bf16 v[34:37], v[154:157], v[170:173], 0
	v_mfma_f32_16x16x32_bf16 v[26:29], v[146:149], v[178:181], 0
	v_mfma_f32_16x16x32_bf16 v[18:21], v[154:157], v[178:181], 0
	v_mfma_f32_16x16x32_bf16 v[10:13], v[146:149], v[186:189], 0
	v_mfma_f32_16x16x32_bf16 v[2:5], v[154:157], v[186:189], 0
	v_mfma_f32_16x16x32_bf16 v[58:61], v[150:153], v[166:169], v[58:61]
	v_mfma_f32_16x16x32_bf16 v[50:53], v[158:161], v[166:169], v[50:53]
	v_mfma_f32_16x16x32_bf16 v[42:45], v[150:153], v[174:177], v[42:45]
	v_mfma_f32_16x16x32_bf16 v[34:37], v[158:161], v[174:177], v[34:37]
	v_mfma_f32_16x16x32_bf16 v[26:29], v[150:153], v[182:185], v[26:29]
	v_mfma_f32_16x16x32_bf16 v[18:21], v[158:161], v[182:185], v[18:21]
	v_mfma_f32_16x16x32_bf16 v[10:13], v[150:153], v[190:193], v[10:13]
	v_mfma_f32_16x16x32_bf16 v[2:5], v[158:161], v[190:193], v[2:5]
	s_barrier
	s_branch .Lpeel1_join

; #define PG8_STAGE(bufoff, gbase, voff) do { _Pragma("unroll") for (int _i = 0; _i < 2; ++_i) \
;         __builtin_amdgcn_global_load_lds((const unsigned*)((const char*)(gbase) + (voff)[_i]), (LAS unsigned*)(lds + (bufoff) + ldsw + _i * 8192), 16, 0, 0); } while (0)
; #define PG8_LDA(dst, b, h) do { _Pragma("unroll") for (int m = 0; m < 4; ++m) _Pragma("unroll") for (int k = 0; k < 2; ++k) dst[m][k] = *(const LAS bf16x8*)(lds + PG8_SA(b, h) + aoff + m * 2048 + k * 1024); } while (0)
; #define PG8_LDB(dst, b, h) do { _Pragma("unroll") for (int n = 0; n < 2; ++n) _Pragma("unroll") for (int k = 0; k < 2; ++k) dst[n][k] = *(const LAS bf16x8*)(lds + PG8_SB(b, h) + boff + n * 2048 + k * 1024); } while (0)
; #define PG8_MMA(ai, bj, At, Bt) do { __builtin_amdgcn_s_setprio(1); _Pragma("unroll") for (int m = 0; m < 4; ++m) _Pragma("unroll") for (int n = 0; n < 2; ++n) _Pragma("unroll") for (int k = 0; k < 2; ++k) \
;         acc[ai][bj][m][n] = __builtin_amdgcn_mfma_f32_16x16x32_bf16(Bt[n][k], At[m][k], acc[ai][bj][m][n], 0, 0, 0); __builtin_amdgcn_s_setprio(0); } while (0)
; #define PG8_WAIT_V(n) asm volatile("s_waitcnt vmcnt(" #n ")" ::: "memory")
; #define PG8_WAIT_L(n) asm volatile("s_waitcnt lgkmcnt(" #n ")" ::: "memory")
; #define PG8_BAR __builtin_amdgcn_s_barrier()
; #define PG8_SCHED __builtin_amdgcn_sched_barrier(0)
; template <class Epi, class Sched>
; __device__ __forceinline__ void gemm_phase(LAS unsigned char* lds, const int lda, const int ldb, const int K, const Sched& S, const Epi& E) {
;     ...
;         for (int t = 0; t < nt; t += 2) {
;             const bool last = (t == nt - 2);
;             const char* a1 = cA + (size_t)(t + 1) * kstep;
;             const char* a2 = last ? nA : cA + (size_t)(t + 2) * kstep; const char* b2 = last ? nB : cB + (size_t)(t + 2) * kstep;
;             const char* a3 = a2 + kstep; const char* b3 = b2 + kstep;
;             PG8_LDB(B0, 0, 0); PG8_LDB(B1, 0, 1); PG8_SCHED; PG8_LDA(At, 0, 0); PG8_STAGE(PG8_SA(1, 1), a1 + hstepA, voffA);
;             PG8_WAIT_V(8); PG8_WAIT_L(0); PG8_BAR; PG8_MMA(0, 0, At, B0); PG8_MMA(0, 1, At, B1); PG8_BAR; PG8_SCHED;
;             PG8_LDA(At, 0, 1); PG8_STAGE(PG8_SB(0, 0), b2, voffB); PG8_STAGE(PG8_SB(0, 1), b2 + hstepB, voffB); PG8_STAGE(PG8_SA(0, 0), a2, voffA);
;             PG8_WAIT_V(8); PG8_WAIT_L(0); PG8_BAR; PG8_MMA(1, 0, At, B0); PG8_MMA(1, 1, At, B1); PG8_BAR; PG8_SCHED;
.LBB0_424:
	s_lshl_b32 s4, s4, 8
	s_ashr_i32 s5, s4, 31
	s_add_u32 s6, s6, 0x40080
	s_addc_u32 s7, s7, 0
	v_lshl_add_u64 v[220:221], s[4:5], 2, v[206:207]
	s_add_u32 s5, s8, 0x100
	s_addc_u32 s51, s9, 0
	s_mov_b32 s69, -2
	v_add_u32_e32 v234, 0x80, v202
	v_add_u32_e32 v235, 0x80, v198
	v_add_u32_e32 v236, 0x80, v204
	v_add_u32_e32 v237, 0x80, v200
	s_cmp_eq_u32 s77, 1
	s_cbranch_scc1 .Lpeel3_first
	s_add_u32 s8, s6, 0xfffc0080
	s_addc_u32 s9, s7, -1
	s_cmp_eq_u32 s69, 12
	s_cselect_b32 s13, s71, s9
	s_cselect_b32 s12, s70, s8
	s_cselect_b32 s15, s73, s51
	s_cselect_b32 s14, s72, s5
	s_add_i32 s81, s63, s36
	ds_read_b128 v[130:133], v222
	ds_read_b128 v[134:137], v222 offset:1024
	ds_read_b128 v[138:141], v222 offset:2048
	ds_read_b128 v[142:145], v222 offset:3072
	ds_read_b128 v[146:149], v223
	ds_read_b128 v[150:153], v223 offset:1024
	ds_read_b128 v[154:157], v223 offset:2048
	ds_read_b128 v[158:161], v223 offset:3072
	s_add_i32 m0, s39, 0xc000
	s_add_i32 s80, s39, 0xe000
	s_add_i32 s82, s81, 0x2000
	s_add_u32 s16, s14, 0x40000
	s_addc_u32 s17, s15, 0
	s_add_i32 s83, s64, s36
	s_add_i32 s84, s83, 0x2000
	s_add_i32 s85, 0, 0x18000
	s_add_i32 s86, 0, 0x1c000
	s_add_u32 s10, s12, 0x40000
	s_addc_u32 s11, s13, 0
	s_add_i32 s75, s85, s36
	s_add_i32 s74, s75, 0x2000
	s_add_u32 s8, s14, 0x40080
	s_addc_u32 s9, s15, 0
	s_add_i32 s79, s86, s36
	s_add_i32 s78, s79, 0x2000
	s_cmp_lg_u32 s69, 12
	ds_read_b128 v[162:165], v224
	ds_read_b128 v[166:169], v224 offset:1024
	ds_read_b128 v[170:173], v224 offset:2048
	ds_read_b128 v[174:177], v224 offset:3072
	ds_read_b128 v[178:181], v224 offset:4096
	ds_read_b128 v[182:185], v224 offset:5120
	ds_read_b128 v[186:189], v224 offset:6144
	ds_read_b128 v[190:193], v224 offset:7168
	global_load_lds_dwordx4 v212, s[6:7]
	s_mov_b32 m0, s80
	s_nop 0
	global_load_lds_dwordx4 v214, s[6:7]
	s_waitcnt vmcnt(24)
	s_waitcnt lgkmcnt(0)
	s_barrier
	v_mfma_f32_16x16x32_bf16 v[126:129], v[130:133], v[162:165], 0
	v_mfma_f32_16x16x32_bf16 v[118:121], v[138:141], v[162:165], 0
	v_mfma_f32_16x16x32_bf16 v[110:113], v[130:133], v[170:173], 0
	v_mfma_f32_16x16x32_bf16 v[102:105], v[138:141], v[170:173], 0
	v_mfma_f32_16x16x32_bf16 v[94:97], v[130:133], v[178:181], 0
	v_mfma_f32_16x16x32_bf16 v[86:89], v[138:141], v[178:181], 0
	v_mfma_f32_16x16x32_bf16 v[78:81], v[130:133], v[186:189], 0
	v_mfma_f32_16x16x32_bf16 v[70:73], v[138:141], v[186:189], 0
	v_mfma_f32_16x16x32_bf16 v[126:129], v[134:137], v[166:169], v[126:129]
	v_mfma_f32_16x16x32_bf16 v[118:121], v[142:145], v[166:169], v[118:121]
	v_mfma_f32_16x16x32_bf16 v[110:113], v[134:137], v[174:177], v[110:113]
	v_mfma_f32_16x16x32_bf16 v[102:105], v[142:145], v[174:177], v[102:105]
	v_mfma_f32_16x16x32_bf16 v[94:97], v[134:137], v[182:185], v[94:97]
	v_mfma_f32_16x16x32_bf16 v[86:89], v[142:145], v[182:185], v[86:89]
	v_mfma_f32_16x16x32_bf16 v[78:81], v[134:137], v[190:193], v[78:81]
	v_mfma_f32_16x16x32_bf16 v[70:73], v[142:145], v[190:193], v[70:73]
	v_mfma_f32_16x16x32_bf16 v[122:125], v[146:149], v[162:165], 0
	v_mfma_f32_16x16x32_bf16 v[114:117], v[154:157], v[162:165], 0
	v_mfma_f32_16x16x32_bf16 v[106:109], v[146:149], v[170:173], 0
	v_mfma_f32_16x16x32_bf16 v[98:101], v[154:157], v[170:173], 0
	v_mfma_f32_16x16x32_bf16 v[90:93], v[146:149], v[178:181], 0
	v_mfma_f32_16x16x32_bf16 v[82:85], v[154:157], v[178:181], 0
	v_mfma_f32_16x16x32_bf16 v[74:77], v[146:149], v[186:189], 0
	v_mfma_f32_16x16x32_bf16 v[66:69], v[154:157], v[186:189], 0
	v_mfma_f32_16x16x32_bf16 v[122:125], v[150:153], v[166:169], v[122:125]
	v_mfma_f32_16x16x32_bf16 v[114:117], v[158:161], v[166:169], v[114:117]
	v_mfma_f32_16x16x32_bf16 v[106:109], v[150:153], v[174:177], v[106:109]
	v_mfma_f32_16x16x32_bf16 v[98:101], v[158:161], v[174:177], v[98:101]
	v_mfma_f32_16x16x32_bf16 v[90:93], v[150:153], v[182:185], v[90:93]
	v_mfma_f32_16x16x32_bf16 v[82:85], v[158:161], v[182:185], v[82:85]
	v_mfma_f32_16x16x32_bf16 v[74:77], v[150:153], v[190:193], v[74:77]
	v_mfma_f32_16x16x32_bf16 v[66:69], v[158:161], v[190:193], v[66:69]
	s_barrier
	s_mov_b32 m0, s81
	ds_read_b128 v[162:165], v224 offset:16384
	ds_read_b128 v[166:169], v224 offset:17408
	ds_read_b128 v[170:173], v224 offset:18432
	ds_read_b128 v[174:177], v224 offset:19456
	ds_read_b128 v[178:181], v224 offset:20480
	ds_read_b128 v[182:185], v224 offset:21504
	ds_read_b128 v[186:189], v224 offset:22528
	ds_read_b128 v[190:193], v224 offset:23552
	global_load_lds_dwordx4 v202, s[14:15]
	s_mov_b32 m0, s82
	s_nop 0
	global_load_lds_dwordx4 v198, s[14:15]
	s_mov_b32 m0, s83
	s_nop 0
	global_load_lds_dwordx4 v202, s[16:17]
	s_mov_b32 m0, s84
	s_nop 0
	global_load_lds_dwordx4 v198, s[16:17]
	s_mov_b32 m0, s39
	s_nop 0
	global_load_lds_dwordx4 v204, s[12:13]
	s_mov_b32 m0, s40
	s_nop 0
	global_load_lds_dwordx4 v200, s[12:13]
	s_waitcnt vmcnt(24)
	s_waitcnt lgkmcnt(0)
	s_barrier
	v_mfma_f32_16x16x32_bf16 v[62:65], v[130:133], v[162:165], 0
	v_mfma_f32_16x16x32_bf16 v[54:57], v[138:141], v[162:165], 0
	v_mfma_f32_16x16x32_bf16 v[46:49], v[130:133], v[170:173], 0
	v_mfma_f32_16x16x32_bf16 v[38:41], v[138:141], v[170:173], 0
	v_mfma_f32_16x16x32_bf16 v[30:33], v[130:133], v[178:181], 0
	v_mfma_f32_16x16x32_bf16 v[22:25], v[138:141], v[178:181], 0
	v_mfma_f32_16x16x32_bf16 v[14:17], v[130:133], v[186:189], 0
	v_mfma_f32_16x16x32_bf16 v[6:9], v[138:141], v[186:189], 0
	v_mfma_f32_16x16x32_bf16 v[62:65], v[134:137], v[166:169], v[62:65]
	v_mfma_f32_16x16x32_bf16 v[54:57], v[142:145], v[166:169], v[54:57]
	v_mfma_f32_16x16x32_bf16 v[46:49], v[134:137], v[174:177], v[46:49]
	v_mfma_f32_16x16x32_bf16 v[38:41], v[142:145], v[174:177], v[38:41]
	v_mfma_f32_16x16x32_bf16 v[30:33], v[134:137], v[182:185], v[30:33]
	v_mfma_f32_16x16x32_bf16 v[22:25], v[142:145], v[182:185], v[22:25]
	v_mfma_f32_16x16x32_bf16 v[14:17], v[134:137], v[190:193], v[14:17]
	v_mfma_f32_16x16x32_bf16 v[6:9], v[142:145], v[190:193], v[6:9]
	v_mfma_f32_16x16x32_bf16 v[58:61], v[146:149], v[162:165], 0
	v_mfma_f32_16x16x32_bf16 v[50:53], v[154:157], v[162:165], 0
	v_mfma_f32_16x16x32_bf16 v[42:45], v[146:149], v[170:173], 0
	v_mfma_f32_16x16x32_bf16 v[34:37], v[154:157], v[170:173], 0
	v_mfma_f32_16x16x32_bf16 v[26:29], v[146:149], v[178:181], 0
	v_mfma_f32_16x16x32_bf16 v[18:21], v[154:157], v[178:181], 0
	v_mfma_f32_16x16x32_bf16 v[10:13], v[146:149], v[186:189], 0
	v_mfma_f32_16x16x32_bf16 v[2:5], v[154:157], v[186:189], 0
	v_mfma_f32_16x16x32_bf16 v[58:61], v[150:153], v[166:169], v[58:61]
	v_mfma_f32_16x16x32_bf16 v[50:53], v[158:161], v[166:169], v[50:53]
	v_mfma_f32_16x16x32_bf16 v[42:45], v[150:153], v[174:177], v[42:45]
	v_mfma_f32_16x16x32_bf16 v[34:37], v[158:161], v[174:177], v[34:37]
	v_mfma_f32_16x16x32_bf16 v[26:29], v[150:153], v[182:185], v[26:29]
	v_mfma_f32_16x16x32_bf16 v[18:21], v[158:161], v[182:185], v[18:21]
	v_mfma_f32_16x16x32_bf16 v[10:13], v[150:153], v[190:193], v[10:13]
	v_mfma_f32_16x16x32_bf16 v[2:5], v[158:161], v[190:193], v[2:5]
	s_barrier
	s_branch .Lpeel3_join
; #define PG8_STAGE(bufoff, gbase, voff) do { _Pragma("unroll") for (int _i = 0; _i < 2; ++_i) \
;         __builtin_amdgcn_global_load_lds((const unsigned*)((const char*)(gbase) + (voff)[_i]), (LAS unsigned*)(lds + (bufoff) + ldsw + _i * 8192), 16, 0, 0); } while (0)
; #define PG8_LDA(dst, b, h) do { _Pragma("unroll") for (int m = 0; m < 4; ++m) _Pragma("unroll") for (int k = 0; k < 2; ++k) dst[m][k] = *(const LAS bf16x8*)(lds + PG8_SA(b, h) + aoff + m * 2048 + k * 1024); } while (0)
; #define PG8_LDB(dst, b, h) do { _Pragma("unroll") for (int n = 0; n < 2; ++n) _Pragma("unroll") for (int k = 0; k < 2; ++k) dst[n][k] = *(const LAS bf16x8*)(lds + PG8_SB(b, h) + boff + n * 2048 + k * 1024); } while (0)
; #define PG8_MMA(ai, bj, At, Bt) do { __builtin_amdgcn_s_setprio(1); _Pragma("unroll") for (int m = 0; m < 4; ++m) _Pragma("unroll") for (int n = 0; n < 2; ++n) _Pragma("unroll") for (int k = 0; k < 2; ++k) \
;         acc[ai][bj][m][n] = __builtin_amdgcn_mfma_f32_16x16x32_bf16(Bt[n][k], At[m][k], acc[ai][bj][m][n], 0, 0, 0); __builtin_amdgcn_s_setprio(0); } while (0)
; #define PG8_WAIT_V(n) asm volatile("s_waitcnt vmcnt(" #n ")" ::: "memory")
; #define PG8_WAIT_L(n) asm volatile("s_waitcnt lgkmcnt(" #n ")" ::: "memory")
; #define PG8_BAR __builtin_amdgcn_s_barrier()
; #define PG8_SCHED __builtin_amdgcn_sched_barrier(0)
; template <class Epi, class Sched>
; __device__ __forceinline__ void gemm_phase(LAS unsigned char* lds, const int lda, const int ldb, const int K, const Sched& S, const Epi& E) {
;     ...
;         for (int t = 0; t < nt; t += 2) {
;             const bool last = (t == nt - 2);
;             const char* a1 = cA + (size_t)(t + 1) * kstep;
;             const char* a2 = last ? nA : cA + (size_t)(t + 2) * kstep; const char* b2 = last ? nB : cB + (size_t)(t + 2) * kstep;
;             const char* a3 = a2 + kstep; const char* b3 = b2 + kstep;
;             PG8_LDB(B0, 0, 0); PG8_LDB(B1, 0, 1); PG8_SCHED; PG8_LDA(At, 0, 0); PG8_STAGE(PG8_SA(1, 1), a1 + hstepA, voffA);
;             PG8_WAIT_V(8); PG8_WAIT_L(0); PG8_BAR; PG8_MMA(0, 0, At, B0); PG8_MMA(0, 1, At, B1); PG8_BAR; PG8_SCHED;
;             PG8_LDA(At, 0, 1); PG8_STAGE(PG8_SB(0, 0), b2, voffB); PG8_STAGE(PG8_SB(0, 1), b2 + hstepB, voffB); PG8_STAGE(PG8_SA(0, 0), a2, voffA);
;             PG8_WAIT_V(8); PG8_WAIT_L(0); PG8_BAR; PG8_MMA(1, 0, At, B0); PG8_MMA(1, 1, At, B1); PG8_BAR; PG8_SCHED;
.Lpeel3_first:
	s_add_u32 s8, s6, 0xfffc0080
	s_addc_u32 s9, s7, -1
	s_cmp_eq_u32 s69, 12
	s_cselect_b32 s13, s71, s9
	s_cselect_b32 s12, s70, s8
	s_cselect_b32 s15, s73, s51
	s_cselect_b32 s14, s72, s5
	s_add_i32 s81, s63, s36
	ds_read_b128 v[130:133], v222
	ds_read_b128 v[134:137], v222 offset:1024
	ds_read_b128 v[138:141], v222 offset:2048
	ds_read_b128 v[142:145], v222 offset:3072
	ds_read_b128 v[146:149], v223
	ds_read_b128 v[150:153], v223 offset:1024
	ds_read_b128 v[154:157], v223 offset:2048
	ds_read_b128 v[158:161], v223 offset:3072
	s_add_i32 m0, s39, 0xc000
	s_add_i32 s80, s39, 0xe000
	s_add_i32 s82, s81, 0x2000
	s_add_u32 s16, s14, 0x40000
	s_addc_u32 s17, s15, 0
	s_add_i32 s83, s64, s36
	s_add_i32 s84, s83, 0x2000
	s_add_i32 s85, 0, 0x18000
	s_add_i32 s86, 0, 0x1c000
	s_add_u32 s10, s12, 0x40000
	s_addc_u32 s11, s13, 0
	s_add_i32 s75, s85, s36
	s_add_i32 s74, s75, 0x2000
	s_add_u32 s8, s14, 0x40080
	s_addc_u32 s9, s15, 0
	s_add_i32 s79, s86, s36
	s_add_i32 s78, s79, 0x2000
	s_cmp_lg_u32 s69, 12
	ds_read_b128 v[162:165], v224
	ds_read_b128 v[166:169], v224 offset:1024
	ds_read_b128 v[170:173], v224 offset:2048
	ds_read_b128 v[174:177], v224 offset:3072
	ds_read_b128 v[178:181], v224 offset:4096
	ds_read_b128 v[182:185], v224 offset:5120
	ds_read_b128 v[186:189], v224 offset:6144
	ds_read_b128 v[190:193], v224 offset:7168
	global_load_lds_dwordx4 v212, s[6:7]
	s_mov_b32 m0, s80
	s_nop 0
	global_load_lds_dwordx4 v214, s[6:7]
	s_waitcnt vmcnt(8)
	s_waitcnt lgkmcnt(0)
	s_barrier
	v_mfma_f32_16x16x32_bf16 v[126:129], v[130:133], v[162:165], 0
	v_mfma_f32_16x16x32_bf16 v[118:121], v[138:141], v[162:165], 0
	v_mfma_f32_16x16x32_bf16 v[110:113], v[130:133], v[170:173], 0
	v_mfma_f32_16x16x32_bf16 v[102:105], v[138:141], v[170:173], 0
	v_mfma_f32_16x16x32_bf16 v[94:97], v[130:133], v[178:181], 0
	v_mfma_f32_16x16x32_bf16 v[86:89], v[138:141], v[178:181], 0
	v_mfma_f32_16x16x32_bf16 v[78:81], v[130:133], v[186:189], 0
	v_mfma_f32_16x16x32_bf16 v[70:73], v[138:141], v[186:189], 0
	v_mfma_f32_16x16x32_bf16 v[126:129], v[134:137], v[166:169], v[126:129]
	v_mfma_f32_16x16x32_bf16 v[118:121], v[142:145], v[166:169], v[118:121]
	v_mfma_f32_16x16x32_bf16 v[110:113], v[134:137], v[174:177], v[110:113]
	v_mfma_f32_16x16x32_bf16 v[102:105], v[142:145], v[174:177], v[102:105]
	v_mfma_f32_16x16x32_bf16 v[94:97], v[134:137], v[182:185], v[94:97]
	v_mfma_f32_16x16x32_bf16 v[86:89], v[142:145], v[182:185], v[86:89]
	v_mfma_f32_16x16x32_bf16 v[78:81], v[134:137], v[190:193], v[78:81]
	v_mfma_f32_16x16x32_bf16 v[70:73], v[142:145], v[190:193], v[70:73]
	v_mfma_f32_16x16x32_bf16 v[122:125], v[146:149], v[162:165], 0
	v_mfma_f32_16x16x32_bf16 v[114:117], v[154:157], v[162:165], 0
	v_mfma_f32_16x16x32_bf16 v[106:109], v[146:149], v[170:173], 0
	v_mfma_f32_16x16x32_bf16 v[98:101], v[154:157], v[170:173], 0
	v_mfma_f32_16x16x32_bf16 v[90:93], v[146:149], v[178:181], 0
	v_mfma_f32_16x16x32_bf16 v[82:85], v[154:157], v[178:181], 0
	v_mfma_f32_16x16x32_bf16 v[74:77], v[146:149], v[186:189], 0
	v_mfma_f32_16x16x32_bf16 v[66:69], v[154:157], v[186:189], 0
	v_mfma_f32_16x16x32_bf16 v[122:125], v[150:153], v[166:169], v[122:125]
	v_mfma_f32_16x16x32_bf16 v[114:117], v[158:161], v[166:169], v[114:117]
	v_mfma_f32_16x16x32_bf16 v[106:109], v[150:153], v[174:177], v[106:109]
	v_mfma_f32_16x16x32_bf16 v[98:101], v[158:161], v[174:177], v[98:101]
	v_mfma_f32_16x16x32_bf16 v[90:93], v[150:153], v[182:185], v[90:93]
	v_mfma_f32_16x16x32_bf16 v[82:85], v[158:161], v[182:185], v[82:85]
	v_mfma_f32_16x16x32_bf16 v[74:77], v[150:153], v[190:193], v[74:77]
	v_mfma_f32_16x16x32_bf16 v[66:69], v[158:161], v[190:193], v[66:69]
	s_barrier
	s_mov_b32 m0, s81
	ds_read_b128 v[162:165], v224 offset:16384
	ds_read_b128 v[166:169], v224 offset:17408
	ds_read_b128 v[170:173], v224 offset:18432
	ds_read_b128 v[174:177], v224 offset:19456
	ds_read_b128 v[178:181], v224 offset:20480
	ds_read_b128 v[182:185], v224 offset:21504
	ds_read_b128 v[186:189], v224 offset:22528
	ds_read_b128 v[190:193], v224 offset:23552
	global_load_lds_dwordx4 v202, s[14:15]
	s_mov_b32 m0, s82
	s_nop 0
	global_load_lds_dwordx4 v198, s[14:15]
	s_mov_b32 m0, s83
	s_nop 0
	global_load_lds_dwordx4 v202, s[16:17]
	s_mov_b32 m0, s84
	s_nop 0
	global_load_lds_dwordx4 v198, s[16:17]
	s_mov_b32 m0, s39
	s_nop 0
	global_load_lds_dwordx4 v204, s[12:13]
	s_mov_b32 m0, s40
	s_nop 0
	global_load_lds_dwordx4 v200, s[12:13]
	s_waitcnt vmcnt(8)
	s_waitcnt lgkmcnt(0)
	s_barrier
	v_mfma_f32_16x16x32_bf16 v[62:65], v[130:133], v[162:165], 0
	v_mfma_f32_16x16x32_bf16 v[54:57], v[138:141], v[162:165], 0
	v_mfma_f32_16x16x32_bf16 v[46:49], v[130:133], v[170:173], 0
	v_mfma_f32_16x16x32_bf16 v[38:41], v[138:141], v[170:173], 0
	v_mfma_f32_16x16x32_bf16 v[30:33], v[130:133], v[178:181], 0
	v_mfma_f32_16x16x32_bf16 v[22:25], v[138:141], v[178:181], 0
	v_mfma_f32_16x16x32_bf16 v[14:17], v[130:133], v[186:189], 0
	v_mfma_f32_16x16x32_bf16 v[6:9], v[138:141], v[186:189], 0
	v_mfma_f32_16x16x32_bf16 v[62:65], v[134:137], v[166:169], v[62:65]
	v_mfma_f32_16x16x32_bf16 v[54:57], v[142:145], v[166:169], v[54:57]
	v_mfma_f32_16x16x32_bf16 v[46:49], v[134:137], v[174:177], v[46:49]
	v_mfma_f32_16x16x32_bf16 v[38:41], v[142:145], v[174:177], v[38:41]
	v_mfma_f32_16x16x32_bf16 v[30:33], v[134:137], v[182:185], v[30:33]
	v_mfma_f32_16x16x32_bf16 v[22:25], v[142:145], v[182:185], v[22:25]
	v_mfma_f32_16x16x32_bf16 v[14:17], v[134:137], v[190:193], v[14:17]
	v_mfma_f32_16x16x32_bf16 v[6:9], v[142:145], v[190:193], v[6:9]
	v_mfma_f32_16x16x32_bf16 v[58:61], v[146:149], v[162:165], 0
	v_mfma_f32_16x16x32_bf16 v[50:53], v[154:157], v[162:165], 0
	v_mfma_f32_16x16x32_bf16 v[42:45], v[146:149], v[170:173], 0
	v_mfma_f32_16x16x32_bf16 v[34:37], v[154:157], v[170:173], 0
	v_mfma_f32_16x16x32_bf16 v[26:29], v[146:149], v[178:181], 0
	v_mfma_f32_16x16x32_bf16 v[18:21], v[154:157], v[178:181], 0
	v_mfma_f32_16x16x32_bf16 v[10:13], v[146:149], v[186:189], 0
	v_mfma_f32_16x16x32_bf16 v[2:5], v[154:157], v[186:189], 0
	v_mfma_f32_16x16x32_bf16 v[58:61], v[150:153], v[166:169], v[58:61]
	v_mfma_f32_16x16x32_bf16 v[50:53], v[158:161], v[166:169], v[50:53]
	v_mfma_f32_16x16x32_bf16 v[42:45], v[150:153], v[174:177], v[42:45]
	v_mfma_f32_16x16x32_bf16 v[34:37], v[158:161], v[174:177], v[34:37]
	v_mfma_f32_16x16x32_bf16 v[26:29], v[150:153], v[182:185], v[26:29]
	v_mfma_f32_16x16x32_bf16 v[18:21], v[158:161], v[182:185], v[18:21]
	v_mfma_f32_16x16x32_bf16 v[10:13], v[150:153], v[190:193], v[10:13]
	v_mfma_f32_16x16x32_bf16 v[2:5], v[158:161], v[190:193], v[2:5]
	s_barrier
	s_branch .Lpeel3_join

; #define PG8_STAGE(bufoff, gbase, voff) do { _Pragma("unroll") for (int _i = 0; _i < 2; ++_i) \
;         __builtin_amdgcn_global_load_lds((const unsigned*)((const char*)(gbase) + (voff)[_i]), (LAS unsigned*)(lds + (bufoff) + ldsw + _i * 8192), 16, 0, 0); } while (0)
; #define PG8_LDA(dst, b, h) do { _Pragma("unroll") for (int m = 0; m < 4; ++m) _Pragma("unroll") for (int k = 0; k < 2; ++k) dst[m][k] = *(const LAS bf16x8*)(lds + PG8_SA(b, h) + aoff + m * 2048 + k * 1024); } while (0)
; #define PG8_LDB(dst, b, h) do { _Pragma("unroll") for (int n = 0; n < 2; ++n) _Pragma("unroll") for (int k = 0; k < 2; ++k) dst[n][k] = *(const LAS bf16x8*)(lds + PG8_SB(b, h) + boff + n * 2048 + k * 1024); } while (0)
; #define PG8_MMA(ai, bj, At, Bt) do { __builtin_amdgcn_s_setprio(1); _Pragma("unroll") for (int m = 0; m < 4; ++m) _Pragma("unroll") for (int n = 0; n < 2; ++n) _Pragma("unroll") for (int k = 0; k < 2; ++k) \
;         acc[ai][bj][m][n] = __builtin_amdgcn_mfma_f32_16x16x32_bf16(Bt[n][k], At[m][k], acc[ai][bj][m][n], 0, 0, 0); __builtin_amdgcn_s_setprio(0); } while (0)
; #define PG8_WAIT_V(n) asm volatile("s_waitcnt vmcnt(" #n ")" ::: "memory")
; #define PG8_WAIT_L(n) asm volatile("s_waitcnt lgkmcnt(" #n ")" ::: "memory")
; #define PG8_BAR __builtin_amdgcn_s_barrier()
; #define PG8_SCHED __builtin_amdgcn_sched_barrier(0)
; template <class Epi, class Sched>
; __device__ __forceinline__ void gemm_phase(LAS unsigned char* lds, const int lda, const int ldb, const int K, const Sched& S, const Epi& E) {
;     ...
;         for (int t = 0; t < nt; t += 2) {
;             const bool last = (t == nt - 2);
;             const char* a1 = cA + (size_t)(t + 1) * kstep;
;             const char* a2 = last ? nA : cA + (size_t)(t + 2) * kstep; const char* b2 = last ? nB : cB + (size_t)(t + 2) * kstep;
;             const char* a3 = a2 + kstep; const char* b3 = b2 + kstep;
;             PG8_LDB(B0, 0, 0); PG8_LDB(B1, 0, 1); PG8_SCHED; PG8_LDA(At, 0, 0); PG8_STAGE(PG8_SA(1, 1), a1 + hstepA, voffA);
;             PG8_WAIT_V(8); PG8_WAIT_L(0); PG8_BAR; PG8_MMA(0, 0, At, B0); PG8_MMA(0, 1, At, B1); PG8_BAR; PG8_SCHED;
;             PG8_LDA(At, 0, 1); PG8_STAGE(PG8_SB(0, 0), b2, voffB); PG8_STAGE(PG8_SB(0, 1), b2 + hstepB, voffB); PG8_STAGE(PG8_SA(0, 0), a2, voffA);
;             PG8_WAIT_V(8); PG8_WAIT_L(0); PG8_BAR; PG8_MMA(1, 0, At, B0); PG8_MMA(1, 1, At, B1); PG8_BAR; PG8_SCHED;
.LBB0_1052:
	s_lshl_b32 s20, s20, 8
	s_ashr_i32 s21, s20, 31
	s_add_u32 s22, s22, 0x40080
	s_addc_u32 s23, s23, 0
	s_add_u32 s13, s24, 0x100
	v_lshl_add_u64 v[214:215], s[20:21], 2, v[204:205]
	s_addc_u32 s15, s25, 0
	s_mov_b32 s21, -2
	v_add_u32_e32 v230, 0x80, v200
	v_add_u32_e32 v231, 0x80, v196
	v_add_u32_e32 v232, 0x80, v202
	v_add_u32_e32 v233, 0x80, v198
	s_cmp_eq_u32 s43, 1
	s_cbranch_scc1 .Lpeel6_first
	s_add_u32 s24, s22, 0xfffc0080
	s_addc_u32 s25, s23, -1
	s_cmp_eq_u32 s21, 12
	s_cselect_b32 s29, s17, s25
	s_cselect_b32 s28, s16, s24
	s_cselect_b32 s31, s19, s15
	s_cselect_b32 s30, s18, s13
	s_add_i32 s70, s50, s36
	s_add_i32 m0, s39, 0xc000
	s_add_i32 s69, s39, 0xe000
	s_add_i32 s71, s70, 0x2000
	s_add_u32 s34, s30, 0x40000
	s_addc_u32 s35, s31, 0
	s_add_i32 s72, s51, s36
	s_add_i32 s73, s72, 0x2000
	s_add_i32 s74, 0, 0x18000
	s_add_i32 s75, 0, 0x1c000
	s_add_u32 s26, s28, 0x40000
	s_addc_u32 s27, s29, 0
	s_add_i32 s66, s74, s36
	s_add_i32 s65, s66, 0x2000
	s_add_u32 s24, s30, 0x40080
	s_addc_u32 s25, s31, 0
	s_add_i32 s68, s75, s36
	s_add_i32 s67, s68, 0x2000
	s_cmp_lg_u32 s21, 12
	global_load_lds_dwordx4 v206, s[22:23]
	s_mov_b32 m0, s69
	s_nop 0
	global_load_lds_dwordx4 v208, s[22:23]
	s_waitcnt vmcnt(16)
	s_waitcnt lgkmcnt(0)
	s_barrier
	v_mfma_f32_16x16x32_bf16 v[126:129], v[130:133], v[162:165], 0
	v_mfma_f32_16x16x32_bf16 v[118:121], v[138:141], v[162:165], 0
	v_mfma_f32_16x16x32_bf16 v[110:113], v[130:133], v[170:173], 0
	v_mfma_f32_16x16x32_bf16 v[102:105], v[138:141], v[170:173], 0
	v_mfma_f32_16x16x32_bf16 v[94:97], v[130:133], v[178:181], 0
	v_mfma_f32_16x16x32_bf16 v[86:89], v[138:141], v[178:181], 0
	v_mfma_f32_16x16x32_bf16 v[78:81], v[130:133], v[186:189], 0
	v_mfma_f32_16x16x32_bf16 v[70:73], v[138:141], v[186:189], 0
	v_mfma_f32_16x16x32_bf16 v[126:129], v[134:137], v[166:169], v[126:129]
	v_mfma_f32_16x16x32_bf16 v[118:121], v[142:145], v[166:169], v[118:121]
	v_mfma_f32_16x16x32_bf16 v[110:113], v[134:137], v[174:177], v[110:113]
	v_mfma_f32_16x16x32_bf16 v[102:105], v[142:145], v[174:177], v[102:105]
	v_mfma_f32_16x16x32_bf16 v[94:97], v[134:137], v[182:185], v[94:97]
	v_mfma_f32_16x16x32_bf16 v[86:89], v[142:145], v[182:185], v[86:89]
	v_mfma_f32_16x16x32_bf16 v[78:81], v[134:137], v[190:193], v[78:81]
	v_mfma_f32_16x16x32_bf16 v[70:73], v[142:145], v[190:193], v[70:73]
	v_mfma_f32_16x16x32_bf16 v[122:125], v[146:149], v[162:165], 0
	v_mfma_f32_16x16x32_bf16 v[114:117], v[154:157], v[162:165], 0
	v_mfma_f32_16x16x32_bf16 v[106:109], v[146:149], v[170:173], 0
	v_mfma_f32_16x16x32_bf16 v[98:101], v[154:157], v[170:173], 0
	v_mfma_f32_16x16x32_bf16 v[90:93], v[146:149], v[178:181], 0
	v_mfma_f32_16x16x32_bf16 v[82:85], v[154:157], v[178:181], 0
	v_mfma_f32_16x16x32_bf16 v[74:77], v[146:149], v[186:189], 0
	v_mfma_f32_16x16x32_bf16 v[66:69], v[154:157], v[186:189], 0
	v_mfma_f32_16x16x32_bf16 v[122:125], v[150:153], v[166:169], v[122:125]
	v_mfma_f32_16x16x32_bf16 v[114:117], v[158:161], v[166:169], v[114:117]
	v_mfma_f32_16x16x32_bf16 v[106:109], v[150:153], v[174:177], v[106:109]
	v_mfma_f32_16x16x32_bf16 v[98:101], v[158:161], v[174:177], v[98:101]
	v_mfma_f32_16x16x32_bf16 v[90:93], v[150:153], v[182:185], v[90:93]
	v_mfma_f32_16x16x32_bf16 v[82:85], v[158:161], v[182:185], v[82:85]
	v_mfma_f32_16x16x32_bf16 v[74:77], v[150:153], v[190:193], v[74:77]
	v_mfma_f32_16x16x32_bf16 v[66:69], v[158:161], v[190:193], v[66:69]
	s_barrier
	s_mov_b32 m0, s70
	ds_read_b128 v[162:165], v219 offset:16384
	ds_read_b128 v[166:169], v219 offset:17408
	ds_read_b128 v[170:173], v219 offset:18432
	ds_read_b128 v[174:177], v219 offset:19456
	ds_read_b128 v[178:181], v219 offset:20480
	ds_read_b128 v[182:185], v219 offset:21504
	ds_read_b128 v[186:189], v219 offset:22528
	ds_read_b128 v[190:193], v219 offset:23552
	global_load_lds_dwordx4 v200, s[30:31]
	s_mov_b32 m0, s71
	s_nop 0
	global_load_lds_dwordx4 v196, s[30:31]
	s_mov_b32 m0, s72
	s_nop 0
	global_load_lds_dwordx4 v200, s[34:35]
	s_mov_b32 m0, s73
	s_nop 0
	global_load_lds_dwordx4 v196, s[34:35]
	s_mov_b32 m0, s39
	s_nop 0
	global_load_lds_dwordx4 v202, s[28:29]
	s_mov_b32 m0, s40
	s_nop 0
	global_load_lds_dwordx4 v198, s[28:29]
	s_waitcnt vmcnt(16)
	s_waitcnt lgkmcnt(0)
	s_barrier
	v_mfma_f32_16x16x32_bf16 v[62:65], v[130:133], v[162:165], 0
	v_mfma_f32_16x16x32_bf16 v[54:57], v[138:141], v[162:165], 0
	v_mfma_f32_16x16x32_bf16 v[46:49], v[130:133], v[170:173], 0
	v_mfma_f32_16x16x32_bf16 v[38:41], v[138:141], v[170:173], 0
	v_mfma_f32_16x16x32_bf16 v[30:33], v[130:133], v[178:181], 0
	v_mfma_f32_16x16x32_bf16 v[22:25], v[138:141], v[178:181], 0
	v_mfma_f32_16x16x32_bf16 v[14:17], v[130:133], v[186:189], 0
	v_mfma_f32_16x16x32_bf16 v[6:9], v[138:141], v[186:189], 0
	v_mfma_f32_16x16x32_bf16 v[62:65], v[134:137], v[166:169], v[62:65]
	v_mfma_f32_16x16x32_bf16 v[54:57], v[142:145], v[166:169], v[54:57]
	v_mfma_f32_16x16x32_bf16 v[46:49], v[134:137], v[174:177], v[46:49]
	v_mfma_f32_16x16x32_bf16 v[38:41], v[142:145], v[174:177], v[38:41]
	v_mfma_f32_16x16x32_bf16 v[30:33], v[134:137], v[182:185], v[30:33]
	v_mfma_f32_16x16x32_bf16 v[22:25], v[142:145], v[182:185], v[22:25]
	v_mfma_f32_16x16x32_bf16 v[14:17], v[134:137], v[190:193], v[14:17]
	v_mfma_f32_16x16x32_bf16 v[6:9], v[142:145], v[190:193], v[6:9]
	v_mfma_f32_16x16x32_bf16 v[58:61], v[146:149], v[162:165], 0
	v_mfma_f32_16x16x32_bf16 v[50:53], v[154:157], v[162:165], 0
	v_mfma_f32_16x16x32_bf16 v[42:45], v[146:149], v[170:173], 0
	v_mfma_f32_16x16x32_bf16 v[34:37], v[154:157], v[170:173], 0
	v_mfma_f32_16x16x32_bf16 v[26:29], v[146:149], v[178:181], 0
	v_mfma_f32_16x16x32_bf16 v[18:21], v[154:157], v[178:181], 0
	v_mfma_f32_16x16x32_bf16 v[10:13], v[146:149], v[186:189], 0
	v_mfma_f32_16x16x32_bf16 v[2:5], v[154:157], v[186:189], 0
	v_mfma_f32_16x16x32_bf16 v[58:61], v[150:153], v[166:169], v[58:61]
	v_mfma_f32_16x16x32_bf16 v[50:53], v[158:161], v[166:169], v[50:53]
	v_mfma_f32_16x16x32_bf16 v[42:45], v[150:153], v[174:177], v[42:45]
	v_mfma_f32_16x16x32_bf16 v[34:37], v[158:161], v[174:177], v[34:37]
	v_mfma_f32_16x16x32_bf16 v[26:29], v[150:153], v[182:185], v[26:29]
	v_mfma_f32_16x16x32_bf16 v[18:21], v[158:161], v[182:185], v[18:21]
	v_mfma_f32_16x16x32_bf16 v[10:13], v[150:153], v[190:193], v[10:13]
	v_mfma_f32_16x16x32_bf16 v[2:5], v[158:161], v[190:193], v[2:5]
	s_barrier
	s_branch .Lpeel6_join
; #define PG8_STAGE(bufoff, gbase, voff) do { _Pragma("unroll") for (int _i = 0; _i < 2; ++_i) \
;         __builtin_amdgcn_global_load_lds((const unsigned*)((const char*)(gbase) + (voff)[_i]), (LAS unsigned*)(lds + (bufoff) + ldsw + _i * 8192), 16, 0, 0); } while (0)
; #define PG8_LDA(dst, b, h) do { _Pragma("unroll") for (int m = 0; m < 4; ++m) _Pragma("unroll") for (int k = 0; k < 2; ++k) dst[m][k] = *(const LAS bf16x8*)(lds + PG8_SA(b, h) + aoff + m * 2048 + k * 1024); } while (0)
; #define PG8_LDB(dst, b, h) do { _Pragma("unroll") for (int n = 0; n < 2; ++n) _Pragma("unroll") for (int k = 0; k < 2; ++k) dst[n][k] = *(const LAS bf16x8*)(lds + PG8_SB(b, h) + boff + n * 2048 + k * 1024); } while (0)
; #define PG8_MMA(ai, bj, At, Bt) do { __builtin_amdgcn_s_setprio(1); _Pragma("unroll") for (int m = 0; m < 4; ++m) _Pragma("unroll") for (int n = 0; n < 2; ++n) _Pragma("unroll") for (int k = 0; k < 2; ++k) \
;         acc[ai][bj][m][n] = __builtin_amdgcn_mfma_f32_16x16x32_bf16(Bt[n][k], At[m][k], acc[ai][bj][m][n], 0, 0, 0); __builtin_amdgcn_s_setprio(0); } while (0)
; #define PG8_WAIT_V(n) asm volatile("s_waitcnt vmcnt(" #n ")" ::: "memory")
; #define PG8_WAIT_L(n) asm volatile("s_waitcnt lgkmcnt(" #n ")" ::: "memory")
; #define PG8_BAR __builtin_amdgcn_s_barrier()
; #define PG8_SCHED __builtin_amdgcn_sched_barrier(0)
; template <class Epi, class Sched>
; __device__ __forceinline__ void gemm_phase(LAS unsigned char* lds, const int lda, const int ldb, const int K, const Sched& S, const Epi& E) {
;     ...
;         for (int t = 0; t < nt; t += 2) {
;             const bool last = (t == nt - 2);
;             const char* a1 = cA + (size_t)(t + 1) * kstep;
;             const char* a2 = last ? nA : cA + (size_t)(t + 2) * kstep; const char* b2 = last ? nB : cB + (size_t)(t + 2) * kstep;
;             const char* a3 = a2 + kstep; const char* b3 = b2 + kstep;
;             PG8_LDB(B0, 0, 0); PG8_LDB(B1, 0, 1); PG8_SCHED; PG8_LDA(At, 0, 0); PG8_STAGE(PG8_SA(1, 1), a1 + hstepA, voffA);
;             PG8_WAIT_V(8); PG8_WAIT_L(0); PG8_BAR; PG8_MMA(0, 0, At, B0); PG8_MMA(0, 1, At, B1); PG8_BAR; PG8_SCHED;
;             PG8_LDA(At, 0, 1); PG8_STAGE(PG8_SB(0, 0), b2, voffB); PG8_STAGE(PG8_SB(0, 1), b2 + hstepB, voffB); PG8_STAGE(PG8_SA(0, 0), a2, voffA);
;             PG8_WAIT_V(8); PG8_WAIT_L(0); PG8_BAR; PG8_MMA(1, 0, At, B0); PG8_MMA(1, 1, At, B1); PG8_BAR; PG8_SCHED;
.Lpeel6_first:
	s_add_u32 s24, s22, 0xfffc0080
	s_addc_u32 s25, s23, -1
	s_cmp_eq_u32 s21, 12
	s_cselect_b32 s29, s17, s25
	s_cselect_b32 s28, s16, s24
	s_cselect_b32 s31, s19, s15
	s_cselect_b32 s30, s18, s13
	s_add_i32 s70, s50, s36
	s_add_i32 m0, s39, 0xc000
	s_add_i32 s69, s39, 0xe000
	s_add_i32 s71, s70, 0x2000
	s_add_u32 s34, s30, 0x40000
	s_addc_u32 s35, s31, 0
	s_add_i32 s72, s51, s36
	s_add_i32 s73, s72, 0x2000
	s_add_i32 s74, 0, 0x18000
	s_add_i32 s75, 0, 0x1c000
	s_add_u32 s26, s28, 0x40000
	s_addc_u32 s27, s29, 0
	s_add_i32 s66, s74, s36
	s_add_i32 s65, s66, 0x2000
	s_add_u32 s24, s30, 0x40080
	s_addc_u32 s25, s31, 0
	s_add_i32 s68, s75, s36
	s_add_i32 s67, s68, 0x2000
	s_cmp_lg_u32 s21, 12
	global_load_lds_dwordx4 v206, s[22:23]
	s_mov_b32 m0, s69
	s_nop 0
	global_load_lds_dwordx4 v208, s[22:23]
	s_waitcnt vmcnt(8)
	s_waitcnt lgkmcnt(0)
	s_barrier
	v_mfma_f32_16x16x32_bf16 v[126:129], v[130:133], v[162:165], 0
	v_mfma_f32_16x16x32_bf16 v[118:121], v[138:141], v[162:165], 0
	v_mfma_f32_16x16x32_bf16 v[110:113], v[130:133], v[170:173], 0
	v_mfma_f32_16x16x32_bf16 v[102:105], v[138:141], v[170:173], 0
	v_mfma_f32_16x16x32_bf16 v[94:97], v[130:133], v[178:181], 0
	v_mfma_f32_16x16x32_bf16 v[86:89], v[138:141], v[178:181], 0
	v_mfma_f32_16x16x32_bf16 v[78:81], v[130:133], v[186:189], 0
	v_mfma_f32_16x16x32_bf16 v[70:73], v[138:141], v[186:189], 0
	v_mfma_f32_16x16x32_bf16 v[126:129], v[134:137], v[166:169], v[126:129]
	v_mfma_f32_16x16x32_bf16 v[118:121], v[142:145], v[166:169], v[118:121]
	v_mfma_f32_16x16x32_bf16 v[110:113], v[134:137], v[174:177], v[110:113]
	v_mfma_f32_16x16x32_bf16 v[102:105], v[142:145], v[174:177], v[102:105]
	v_mfma_f32_16x16x32_bf16 v[94:97], v[134:137], v[182:185], v[94:97]
	v_mfma_f32_16x16x32_bf16 v[86:89], v[142:145], v[182:185], v[86:89]
	v_mfma_f32_16x16x32_bf16 v[78:81], v[134:137], v[190:193], v[78:81]
	v_mfma_f32_16x16x32_bf16 v[70:73], v[142:145], v[190:193], v[70:73]
	v_mfma_f32_16x16x32_bf16 v[122:125], v[146:149], v[162:165], 0
	v_mfma_f32_16x16x32_bf16 v[114:117], v[154:157], v[162:165], 0
	v_mfma_f32_16x16x32_bf16 v[106:109], v[146:149], v[170:173], 0
	v_mfma_f32_16x16x32_bf16 v[98:101], v[154:157], v[170:173], 0
	v_mfma_f32_16x16x32_bf16 v[90:93], v[146:149], v[178:181], 0
	v_mfma_f32_16x16x32_bf16 v[82:85], v[154:157], v[178:181], 0
	v_mfma_f32_16x16x32_bf16 v[74:77], v[146:149], v[186:189], 0
	v_mfma_f32_16x16x32_bf16 v[66:69], v[154:157], v[186:189], 0
	v_mfma_f32_16x16x32_bf16 v[122:125], v[150:153], v[166:169], v[122:125]
	v_mfma_f32_16x16x32_bf16 v[114:117], v[158:161], v[166:169], v[114:117]
	v_mfma_f32_16x16x32_bf16 v[106:109], v[150:153], v[174:177], v[106:109]
	v_mfma_f32_16x16x32_bf16 v[98:101], v[158:161], v[174:177], v[98:101]
	v_mfma_f32_16x16x32_bf16 v[90:93], v[150:153], v[182:185], v[90:93]
	v_mfma_f32_16x16x32_bf16 v[82:85], v[158:161], v[182:185], v[82:85]
	v_mfma_f32_16x16x32_bf16 v[74:77], v[150:153], v[190:193], v[74:77]
	v_mfma_f32_16x16x32_bf16 v[66:69], v[158:161], v[190:193], v[66:69]
	s_barrier
	s_mov_b32 m0, s70
	ds_read_b128 v[162:165], v219 offset:16384
	ds_read_b128 v[166:169], v219 offset:17408
	ds_read_b128 v[170:173], v219 offset:18432
	ds_read_b128 v[174:177], v219 offset:19456
	ds_read_b128 v[178:181], v219 offset:20480
	ds_read_b128 v[182:185], v219 offset:21504
	ds_read_b128 v[186:189], v219 offset:22528
	ds_read_b128 v[190:193], v219 offset:23552
	global_load_lds_dwordx4 v200, s[30:31]
	s_mov_b32 m0, s71
	s_nop 0
	global_load_lds_dwordx4 v196, s[30:31]
	s_mov_b32 m0, s72
	s_nop 0
	global_load_lds_dwordx4 v200, s[34:35]
	s_mov_b32 m0, s73
	s_nop 0
	global_load_lds_dwordx4 v196, s[34:35]
	s_mov_b32 m0, s39
	s_nop 0
	global_load_lds_dwordx4 v202, s[28:29]
	s_mov_b32 m0, s40
	s_nop 0
	global_load_lds_dwordx4 v198, s[28:29]
	s_waitcnt vmcnt(8)
	s_waitcnt lgkmcnt(0)
	s_barrier
	v_mfma_f32_16x16x32_bf16 v[62:65], v[130:133], v[162:165], 0
	v_mfma_f32_16x16x32_bf16 v[54:57], v[138:141], v[162:165], 0
	v_mfma_f32_16x16x32_bf16 v[46:49], v[130:133], v[170:173], 0
	v_mfma_f32_16x16x32_bf16 v[38:41], v[138:141], v[170:173], 0
	v_mfma_f32_16x16x32_bf16 v[30:33], v[130:133], v[178:181], 0
	v_mfma_f32_16x16x32_bf16 v[22:25], v[138:141], v[178:181], 0
	v_mfma_f32_16x16x32_bf16 v[14:17], v[130:133], v[186:189], 0
	v_mfma_f32_16x16x32_bf16 v[6:9], v[138:141], v[186:189], 0
	v_mfma_f32_16x16x32_bf16 v[62:65], v[134:137], v[166:169], v[62:65]
	v_mfma_f32_16x16x32_bf16 v[54:57], v[142:145], v[166:169], v[54:57]
	v_mfma_f32_16x16x32_bf16 v[46:49], v[134:137], v[174:177], v[46:49]
	v_mfma_f32_16x16x32_bf16 v[38:41], v[142:145], v[174:177], v[38:41]
	v_mfma_f32_16x16x32_bf16 v[30:33], v[134:137], v[182:185], v[30:33]
	v_mfma_f32_16x16x32_bf16 v[22:25], v[142:145], v[182:185], v[22:25]
	v_mfma_f32_16x16x32_bf16 v[14:17], v[134:137], v[190:193], v[14:17]
	v_mfma_f32_16x16x32_bf16 v[6:9], v[142:145], v[190:193], v[6:9]
	v_mfma_f32_16x16x32_bf16 v[58:61], v[146:149], v[162:165], 0
	v_mfma_f32_16x16x32_bf16 v[50:53], v[154:157], v[162:165], 0
	v_mfma_f32_16x16x32_bf16 v[42:45], v[146:149], v[170:173], 0
	v_mfma_f32_16x16x32_bf16 v[34:37], v[154:157], v[170:173], 0
	v_mfma_f32_16x16x32_bf16 v[26:29], v[146:149], v[178:181], 0
	v_mfma_f32_16x16x32_bf16 v[18:21], v[154:157], v[178:181], 0
	v_mfma_f32_16x16x32_bf16 v[10:13], v[146:149], v[186:189], 0
	v_mfma_f32_16x16x32_bf16 v[2:5], v[154:157], v[186:189], 0
	v_mfma_f32_16x16x32_bf16 v[58:61], v[150:153], v[166:169], v[58:61]
	v_mfma_f32_16x16x32_bf16 v[50:53], v[158:161], v[166:169], v[50:53]
	v_mfma_f32_16x16x32_bf16 v[42:45], v[150:153], v[174:177], v[42:45]
	v_mfma_f32_16x16x32_bf16 v[34:37], v[158:161], v[174:177], v[34:37]
	v_mfma_f32_16x16x32_bf16 v[26:29], v[150:153], v[182:185], v[26:29]
	v_mfma_f32_16x16x32_bf16 v[18:21], v[158:161], v[182:185], v[18:21]
	v_mfma_f32_16x16x32_bf16 v[10:13], v[150:153], v[190:193], v[10:13]
	v_mfma_f32_16x16x32_bf16 v[2:5], v[158:161], v[190:193], v[2:5]
	s_barrier
	s_branch .Lpeel6_join
